# NSA selected branch made workgroup-cooperative: each selected 64-key block is staged once per 16-token item through LDS (double-buffered) and scored per wave only where its tokens selected it; halves
# speedup vs baseline: 1.2461x; 1.0574x over previous
; #define WAVE_SYNC() do { __builtin_amdgcn_fence(__ATOMIC_RELEASE, "wavefront"); __builtin_amdgcn_wave_barrier(); __builtin_amdgcn_fence(__ATOMIC_ACQUIRE, "wavefront"); } while (0)
; DI void nsa_group(const Params& p, int t0, float* wl) {
;     ...
;   const unsigned long long ulo = mlo[0] | mlo[1] | mlo[2] | mlo[3], uhi = mhi[0] | mhi[1] | mhi[2] | mhi[3];
;   const int nlo = __popcll(ulo), nblk = nlo + __popcll(uhi);
;   { const unsigned long long below = (1ull << lane) - 1ull;
;     if ((ulo >> lane) & 1ull) { int tm = 0;
; #pragma unroll
;       for (int t2 = 0; t2 < 4; ++t2) tm |= (int)((mlo[t2] >> lane) & 1ull) << t2;
;       blist[__popcll(ulo & below)] = lane | (tm << 8); }
;     if ((uhi >> lane) & 1ull) { int tm = 0;
; #pragma unroll
;       for (int t2 = 0; t2 < 4; ++t2) tm |= (int)((mhi[t2] >> lane) & 1ull) << t2;
;       blist[nlo + __popcll(uhi & below)] = (lane + 64) | (tm << 8); } }
;   WAVE_SYNC();
;   float m2 = -1e30f, l2 = 0.f; f32x4 Os[4];
; #pragma unroll
;   for (int dt = 0; dt < 4; ++dt) Os[dt] = (f32x4){0.f, 0.f, 0.f, 0.f};
;   const int nh = 2 * nblk;
;   SelRegs r0, r1;
;   { const int e0 = __builtin_amdgcn_readfirstlane(blist[0]); sel_issue(r0, projb + (size_t)((e0 & 255) * 64) * LDP + C_NKS, LDP, vsT + (e0 & 255) * 64, VLD, rowa, l15, quad); }
;   for (int hs = 0; hs < nh; hs += 2) {
;     const int e = __builtin_amdgcn_readfirstlane(blist[hs >> 1]); const int kb0 = (e & 255) * 64; const bool colsel = ((e >> (8 + tk)) & 1) != 0;
;     sel_wait(r0);
;     sel_issue(r1, projb + (size_t)(kb0 + 32) * LDP + C_NKS, LDP, vsT + kb0 + 32, VLD, rowa, l15, quad);
;     sel_compute(r0, qf, kb0, colsel, stk, quad, m2, l2, Os);
;     sel_wait(r1);
;     { const int en = __builtin_amdgcn_readfirstlane(blist[(hs + 2 < nh ? hs + 2 : hs) >> 1]); sel_issue(r0, projb + (size_t)((en & 255) * 64) * LDP + C_NKS, LDP, vsT + (en & 255) * 64, VLD, rowa, l15, quad); }
;     sel_compute(r1, qf, kb0 + 32, colsel, stk, quad, m2, l2, Os);
;   }
.LBB0_485:
	s_or_b64 exec, exec, s[0:1]
	v_lshl_add_u32 v128, v177, 2, v120
	ds_read_b32 v210, v128 offset:4224
	v_bcnt_u32_b32 v129, v32, 0
	v_bcnt_u32_b32 v129, v33, v129
	v_add_u32_e32 v129, v129, v34
	v_mov_b32_e32 v24, 0
	v_mov_b32_e32 v25, 0
	v_mov_b32_e32 v26, 0
	v_mov_b32_e32 v27, 0
	v_mov_b32_e32 v28, 0
	v_mov_b32_e32 v29, 0
	v_mov_b32_e32 v30, 0
	v_mov_b32_e32 v31, 0
	v_mov_b32_e32 v32, 0
	v_mov_b32_e32 v33, 0
	v_mov_b32_e32 v34, 0
	v_mov_b32_e32 v35, 0
	v_mov_b32_e32 v36, 0
	v_mov_b32_e32 v37, 0
	v_mov_b32_e32 v38, 0
	v_mov_b32_e32 v39, 0
	v_mov_b32_e32 v131, 0
	v_readfirstlane_b32 s9, v129
	v_lshrrev_b32_e32 v133, 6, v170
	v_readfirstlane_b32 s20, v110
	v_readfirstlane_b32 s21, v111
	s_add_u32 s20, s20, 0x1100
	s_addc_u32 s21, s21, 0
	v_readlane_b32 s0, v244, 19
	v_readlane_b32 s1, v244, 20
	v_readfirstlane_b32 s2, v104
	s_lshl_b32 s2, s2, 1
	s_add_u32 s22, s0, s2
	s_addc_u32 s23, s1, 0
	v_readfirstlane_b32 s4, v133
	s_lshl_b32 s4, s4, 2
	s_mov_b32 s6, 0x3e38aa3b
	v_mul_u32_u24_e32 v95, 0x90, v100
	v_add_u32_e32 v95, v95, v112
	v_mul_u32_u24_e32 v96, 0x90, v88
	v_add_u32_e32 v96, v96, v112
	v_sub_u32_e32 v236, v106, v124
	v_lshlrev_b32_e64 v238, v91, 1
	v_mov_b32_e32 v240, 0xff800000
	v_mov_b32_e32 v132, v189
	v_lshrrev_b32_e32 v128, 3, v170
	v_and_b32_e32 v133, 7, v170
	s_movk_i32 s0, 0x1a00
	v_mul_u32_u24_e32 v90, s0, v128
	v_lshl_add_u32 v90, v133, 4, v90
	v_add_u32_e32 v91, 0x34000, v90
	s_mov_b32 s0, 0x8100
	v_mul_lo_u32 v92, v128, s0
	v_lshl_add_u32 v92, v133, 4, v92
	v_add_u32_e32 v93, 0x102000, v92
	v_mul_u32_u24_e32 v94, 0x90, v128
	v_lshl_add_u32 v94, v133, 4, v94
	v_lshlrev_b32_e32 v128, 2, v177
	ds_write_b32 v128, v143 offset:18432
	ds_write_b32 v128, v143 offset:18688
	s_waitcnt lgkmcnt(0)
	s_barrier
	v_cmp_gt_u32_e32 vcc, s9, v177
	s_and_saveexec_b64 s[12:13], vcc
	v_and_b32_e32 v129, 0xff, v210
	v_lshlrev_b32_e32 v129, 2, v129
	v_bfe_u32 v133, v210, 8, 4
	v_lshlrev_b32_e32 v133, s4, v133
	ds_or_b32 v129, v133 offset:18432
	s_mov_b64 exec, s[12:13]
	s_waitcnt lgkmcnt(0)
	s_barrier
	ds_read_b32 v88, v128 offset:18432
	ds_read_b32 v89, v128 offset:18688
	s_waitcnt lgkmcnt(0)
	v_cmp_ne_u32_e64 s[48:49], 0, v88
	v_cmp_ne_u32_e64 s[58:59], 0, v89
	s_mov_b32 s7, 0
	s_nop 1
	s_cmp_lg_u64 s[48:49], 0
	s_cbranch_scc0 .Lsc_hi_1
	s_ff1_i32_b64 s5, s[48:49]
	s_bitset0_b64 s[48:49], s5
	s_branch .Lsc_fn_1
.Lsc_hi_1:
	s_cmp_lg_u64 s[58:59], 0
	s_cbranch_scc0 .Lsc_none_1
	s_ff1_i32_b64 s5, s[58:59]
	s_bitset0_b64 s[58:59], s5
	s_add_i32 s5, s5, 64
	s_branch .Lsc_fn_1
.Lsc_none_1:
	s_mov_b32 s5, -1
.Lsc_fn_1:
	s_mul_i32 s0, s5, 0x68000
	s_add_u32 s24, s20, s0
	s_addc_u32 s25, s21, 0
	s_lshl_b32 s0, s5, 7
	s_add_u32 s38, s22, s0
	s_addc_u32 s39, s23, 0
	global_load_dwordx4 v[72:75], v90, s[24:25]
	global_load_dwordx4 v[76:79], v91, s[24:25]
	global_load_dwordx4 v[80:83], v92, s[38:39]
	global_load_dwordx4 v[84:87], v93, s[38:39]
	v_mov_b32_e32 v99, v94
	s_waitcnt vmcnt(0)
	ds_write_b128 v99, v[72:75] offset:20480
	ds_write_b128 v99, v[76:79] offset:25088
	ds_write_b128 v99, v[80:83] offset:29696
	ds_write_b128 v99, v[84:87] offset:34304
	s_waitcnt lgkmcnt(0)
	s_barrier
.Lsc_loop:
	s_cmp_lg_u64 s[48:49], 0
	s_cbranch_scc0 .Lsc_hi_2
	s_ff1_i32_b64 s8, s[48:49]
	s_bitset0_b64 s[48:49], s8
	s_branch .Lsc_fn_2
.Lsc_hi_2:
	s_cmp_lg_u64 s[58:59], 0
	s_cbranch_scc0 .Lsc_none_2
	s_ff1_i32_b64 s8, s[58:59]
	s_bitset0_b64 s[58:59], s8
	s_add_i32 s8, s8, 64
	s_branch .Lsc_fn_2
.Lsc_none_2:
	s_mov_b32 s8, -1
.Lsc_fn_2:
	s_cmp_lt_i32 s8, 0
	s_cbranch_scc1 .Lsc_noload
	s_mul_i32 s0, s8, 0x68000
	s_add_u32 s24, s20, s0
	s_addc_u32 s25, s21, 0
	s_lshl_b32 s0, s8, 7
	s_add_u32 s38, s22, s0
	s_addc_u32 s39, s23, 0
	global_load_dwordx4 v[72:75], v90, s[24:25]
	global_load_dwordx4 v[76:79], v91, s[24:25]
	global_load_dwordx4 v[80:83], v92, s[38:39]
	global_load_dwordx4 v[84:87], v93, s[38:39]
.Lsc_noload:
	s_and_b32 s1, s5, 63
	v_readlane_b32 s0, v88, s1
	v_readlane_b32 s2, v89, s1
	s_cmp_lt_u32 s5, 64
	s_cselect_b32 s0, s0, s2
	s_lshr_b32 s0, s0, s4
	s_and_b32 s9, s0, 15
	s_cmp_eq_u32 s9, 0
	s_cbranch_scc1 .Lsc_skip
	v_add_u32_e32 v97, s7, v95
	v_add_u32_e32 v98, s7, v96
	ds_read_b128 v[40:43], v97 offset:20480
	ds_read_b128 v[44:47], v97 offset:21056
	ds_read_b128 v[48:51], v97 offset:20544
	ds_read_b128 v[52:55], v97 offset:21120
	ds_read_b128 v[56:59], v98 offset:29696
	ds_read_b128 v[60:63], v98 offset:32000
	ds_read_b128 v[64:67], v98 offset:34304
	ds_read_b128 v[68:71], v98 offset:36608
	s_lshl_b32 s12, s5, 6
	s_waitcnt lgkmcnt(4)
	v_mfma_f32_16x16x32_bf16 v[150:153], v[40:43], v[4:7], 0
	v_mfma_f32_16x16x32_bf16 v[154:157], v[44:47], v[4:7], 0
	v_mfma_f32_16x16x32_bf16 v[150:153], v[48:51], v[8:11], v[150:153]
	v_mfma_f32_16x16x32_bf16 v[154:157], v[52:55], v[8:11], v[154:157]
	v_and_b32_e32 v134, s9, v238
	v_cmp_ne_u32_e32 vcc, 0, v134
	v_subrev_u32_e32 v129, s12, v236
	s_nop 1
	v_cndmask_b32_e32 v134, -1, v129, vcc
	v_cmp_le_i32_e64 s[40:41], 0, v134
	v_cmp_le_i32_e64 s[42:43], 1, v134
	v_cmp_le_i32_e64 s[44:45], 2, v134
	v_cmp_le_i32_e64 s[46:47], 3, v134
	v_cndmask_b32_e64 v158, v240, 0, s[40:41]
	v_cndmask_b32_e64 v159, v240, 0, s[42:43]
	v_cndmask_b32_e64 v160, v240, 0, s[44:45]
	v_cndmask_b32_e64 v161, v240, 0, s[46:47]
	v_cmp_le_i32_e64 s[40:41], 4, v134
	v_cmp_le_i32_e64 s[42:43], 5, v134
	v_cmp_le_i32_e64 s[44:45], 6, v134
	v_cmp_le_i32_e64 s[46:47], 7, v134
	v_cndmask_b32_e64 v162, v240, 0, s[40:41]
	v_cndmask_b32_e64 v163, v240, 0, s[42:43]
	v_cndmask_b32_e64 v164, v240, 0, s[44:45]
	v_cndmask_b32_e64 v165, v240, 0, s[46:47]
	v_fma_f32 v150, v150, s6, v158
	v_fma_f32 v151, v151, s6, v159
	v_fma_f32 v152, v152, s6, v160
	v_fma_f32 v153, v153, s6, v161
	v_fma_f32 v154, v154, s6, v162
	v_fma_f32 v155, v155, s6, v163
	v_fma_f32 v156, v156, s6, v164
	v_fma_f32 v157, v157, s6, v165
	v_max3_f32 v128, v150, v151, v152
	v_max3_f32 v129, v153, v154, v155
	v_max3_f32 v133, v156, v157, v132
	v_max3_f32 v128, v128, v129, v133
	ds_bpermute_b32 v129, v125, v128
	s_waitcnt lgkmcnt(0)
; DI bf16_t f2bf(float f) { unsigned u = __float_as_uint(f); u += 0x7fffu + ((u >> 16) & 1u); return (bf16_t)(u >> 16); }
; DI float fexp(float x) { return __builtin_amdgcn_exp2f(x * 1.4426950408889634f); }
; DI void sel_compute(const SelRegs& rg, const bf16x8 (&qf)[2], int kb0, bool colsel, int stk, int quad, float& m, float& lsum, f32x4 (&Os)[4]) {
;   f32x4 sa = {0.f, 0.f, 0.f, 0.f}, sb = {0.f, 0.f, 0.f, 0.f};
; #pragma unroll
;   for (int ks = 0; ks < 2; ++ks) { sa = MFMA16(__builtin_bit_cast(bf16x8, rg.ka[ks]), qf[ks], sa); sb = MFMA16(__builtin_bit_cast(bf16x8, rg.kb[ks]), qf[ks], sb); }
;   float mx = m;
; #pragma unroll
;   for (int i = 0; i < 4; ++i) { const int ka = kb0 + 8 * quad + i;
;     const float va = (colsel && ka <= stk) ? sa[i] * 0.125f : -1e30f, vb = (colsel && ka + 4 <= stk) ? sb[i] * 0.125f : -1e30f;
;     sa[i] = va; sb[i] = vb; mx = fmaxf(mx, fmaxf(va, vb)); }
;   mx = fmaxf(mx, __shfl_xor(mx, 16)); mx = fmaxf(mx, __shfl_xor(mx, 32));
;   const float corr = fexp(m - mx); m = mx; float ps = 0.f;
; #pragma unroll
;   for (int i = 0; i < 4; ++i) { const float pa = sa[i] > -1e29f ? fexp(sa[i] - mx) : 0.f, pb = sb[i] > -1e29f ? fexp(sb[i] - mx) : 0.f; sa[i] = pa; sb[i] = pb; ps += pa + pb; }
;   lsum = lsum * corr + ps;
;   bf16x8 pf;
; #pragma unroll
;   for (int i = 0; i < 4; ++i) { pf[i] = (short)f2bf(sa[i]); pf[4 + i] = (short)f2bf(sb[i]); }
; #pragma unroll
;   for (int dt = 0; dt < 4; ++dt) { Os[dt][0] *= corr; Os[dt][1] *= corr; Os[dt][2] *= corr; Os[dt][3] *= corr; Os[dt] = MFMA16(__builtin_bit_cast(bf16x8, rg.v[dt]), pf, Os[dt]); }
; DI void nsa_group(const Params& p, int t0, float* wl) {
;     ...
;   for (int hs = 0; hs < nh; hs += 2) {
;     const int e = __builtin_amdgcn_readfirstlane(blist[hs >> 1]); const int kb0 = (e & 255) * 64; const bool colsel = ((e >> (8 + tk)) & 1) != 0;
;     sel_wait(r0);
;     sel_issue(r1, projb + (size_t)(kb0 + 32) * LDP + C_NKS, LDP, vsT + kb0 + 32, VLD, rowa, l15, quad);
;     sel_compute(r0, qf, kb0, colsel, stk, quad, m2, l2, Os);
;     sel_wait(r1);
;     { const int en = __builtin_amdgcn_readfirstlane(blist[(hs + 2 < nh ? hs + 2 : hs) >> 1]); sel_issue(r0, projb + (size_t)((en & 255) * 64) * LDP + C_NKS, LDP, vsT + (en & 255) * 64, VLD, rowa, l15, quad); }
;     sel_compute(r1, qf, kb0 + 32, colsel, stk, quad, m2, l2, Os);
;   }
	v_max_f32_e32 v128, v128, v129
	ds_bpermute_b32 v129, v126, v128
	s_waitcnt lgkmcnt(0)
	v_max_f32_e32 v128, v128, v129
	v_sub_f32_e32 v130, v132, v128
	v_exp_f32_e32 v130, v130
	v_mov_b32_e32 v132, v128
	v_sub_f32_e32 v150, v150, v128
	v_sub_f32_e32 v151, v151, v128
	v_sub_f32_e32 v152, v152, v128
	v_sub_f32_e32 v153, v153, v128
	v_sub_f32_e32 v154, v154, v128
	v_sub_f32_e32 v155, v155, v128
	v_sub_f32_e32 v156, v156, v128
	v_sub_f32_e32 v157, v157, v128
	v_exp_f32_e32 v150, v150
	v_exp_f32_e32 v151, v151
	v_exp_f32_e32 v152, v152
	v_exp_f32_e32 v153, v153
	v_exp_f32_e32 v154, v154
	v_exp_f32_e32 v155, v155
	v_exp_f32_e32 v156, v156
	v_exp_f32_e32 v157, v157
	v_pk_mul_f32 v[36:37], v[36:37], v[130:131] op_sel_hi:[1,0]
	v_pk_mul_f32 v[38:39], v[38:39], v[130:131] op_sel_hi:[1,0]
	v_pk_mul_f32 v[32:33], v[32:33], v[130:131] op_sel_hi:[1,0]
	v_pk_mul_f32 v[34:35], v[34:35], v[130:131] op_sel_hi:[1,0]
	v_pk_mul_f32 v[28:29], v[28:29], v[130:131] op_sel_hi:[1,0]
	v_pk_mul_f32 v[30:31], v[30:31], v[130:131] op_sel_hi:[1,0]
	v_pk_mul_f32 v[24:25], v[24:25], v[130:131] op_sel_hi:[1,0]
	v_pk_mul_f32 v[26:27], v[26:27], v[130:131] op_sel_hi:[1,0]
	v_add_f32_e32 v129, v150, v151
	v_add_f32_e32 v133, v152, v153
	v_add_f32_e32 v129, v129, v154
	v_add_f32_e32 v133, v133, v155
	v_add_f32_e32 v129, v129, v156
	v_add_f32_e32 v133, v133, v157
	v_add_f32_e32 v129, v129, v133
	v_fma_f32 v131, v131, v130, v129
	v_cvt_pk_bf16_f32 v166, v150, v151
	v_cvt_pk_bf16_f32 v167, v152, v153
	v_cvt_pk_bf16_f32 v168, v154, v155
	v_cvt_pk_bf16_f32 v169, v156, v157
	s_nop 1
	v_mfma_f32_16x16x32_bf16 v[36:39], v[56:59], v[166:169], v[36:39]
	v_mfma_f32_16x16x32_bf16 v[32:35], v[60:63], v[166:169], v[32:35]
	v_mfma_f32_16x16x32_bf16 v[28:31], v[64:67], v[166:169], v[28:31]
	v_mfma_f32_16x16x32_bf16 v[24:27], v[68:71], v[166:169], v[24:27]
	ds_read_b128 v[40:43], v97 offset:25088
	ds_read_b128 v[44:47], v97 offset:25664
	ds_read_b128 v[48:51], v97 offset:25152
	ds_read_b128 v[52:55], v97 offset:25728
	ds_read_b128 v[56:59], v98 offset:29760
	ds_read_b128 v[60:63], v98 offset:32064
	ds_read_b128 v[64:67], v98 offset:34368
	ds_read_b128 v[68:71], v98 offset:36672
	s_lshl_b32 s12, s5, 6
	s_add_i32 s12, s12, 32
	s_waitcnt lgkmcnt(4)
	v_mfma_f32_16x16x32_bf16 v[150:153], v[40:43], v[4:7], 0
	v_mfma_f32_16x16x32_bf16 v[154:157], v[44:47], v[4:7], 0
	v_mfma_f32_16x16x32_bf16 v[150:153], v[48:51], v[8:11], v[150:153]
	v_mfma_f32_16x16x32_bf16 v[154:157], v[52:55], v[8:11], v[154:157]
	v_and_b32_e32 v134, s9, v238
	v_cmp_ne_u32_e32 vcc, 0, v134
	v_subrev_u32_e32 v129, s12, v236
	s_nop 1
	v_cndmask_b32_e32 v134, -1, v129, vcc
	v_cmp_le_i32_e64 s[40:41], 0, v134
	v_cmp_le_i32_e64 s[42:43], 1, v134
	v_cmp_le_i32_e64 s[44:45], 2, v134
	v_cmp_le_i32_e64 s[46:47], 3, v134
	v_cndmask_b32_e64 v158, v240, 0, s[40:41]
	v_cndmask_b32_e64 v159, v240, 0, s[42:43]
	v_cndmask_b32_e64 v160, v240, 0, s[44:45]
	v_cndmask_b32_e64 v161, v240, 0, s[46:47]
	v_cmp_le_i32_e64 s[40:41], 4, v134
	v_cmp_le_i32_e64 s[42:43], 5, v134
	v_cmp_le_i32_e64 s[44:45], 6, v134
	v_cmp_le_i32_e64 s[46:47], 7, v134
	v_cndmask_b32_e64 v162, v240, 0, s[40:41]
	v_cndmask_b32_e64 v163, v240, 0, s[42:43]
	v_cndmask_b32_e64 v164, v240, 0, s[44:45]
	v_cndmask_b32_e64 v165, v240, 0, s[46:47]
	v_fma_f32 v150, v150, s6, v158
	v_fma_f32 v151, v151, s6, v159
	v_fma_f32 v152, v152, s6, v160
	v_fma_f32 v153, v153, s6, v161
	v_fma_f32 v154, v154, s6, v162
	v_fma_f32 v155, v155, s6, v163
	v_fma_f32 v156, v156, s6, v164
	v_fma_f32 v157, v157, s6, v165
	v_max3_f32 v128, v150, v151, v152
	v_max3_f32 v129, v153, v154, v155
	v_max3_f32 v133, v156, v157, v132
	v_max3_f32 v128, v128, v129, v133
	ds_bpermute_b32 v129, v125, v128
	s_waitcnt lgkmcnt(0)
	v_max_f32_e32 v128, v128, v129
	ds_bpermute_b32 v129, v126, v128
	s_waitcnt lgkmcnt(0)
	v_max_f32_e32 v128, v128, v129
	v_sub_f32_e32 v130, v132, v128
	v_exp_f32_e32 v130, v130
	v_mov_b32_e32 v132, v128
	v_sub_f32_e32 v150, v150, v128
	v_sub_f32_e32 v151, v151, v128
	v_sub_f32_e32 v152, v152, v128
	v_sub_f32_e32 v153, v153, v128
	v_sub_f32_e32 v154, v154, v128
	v_sub_f32_e32 v155, v155, v128
	v_sub_f32_e32 v156, v156, v128
	v_sub_f32_e32 v157, v157, v128
	v_exp_f32_e32 v150, v150
	v_exp_f32_e32 v151, v151
	v_exp_f32_e32 v152, v152
	v_exp_f32_e32 v153, v153
	v_exp_f32_e32 v154, v154
	v_exp_f32_e32 v155, v155
	v_exp_f32_e32 v156, v156
	v_exp_f32_e32 v157, v157
	v_pk_mul_f32 v[36:37], v[36:37], v[130:131] op_sel_hi:[1,0]
	v_pk_mul_f32 v[38:39], v[38:39], v[130:131] op_sel_hi:[1,0]
	v_pk_mul_f32 v[32:33], v[32:33], v[130:131] op_sel_hi:[1,0]
	v_pk_mul_f32 v[34:35], v[34:35], v[130:131] op_sel_hi:[1,0]
	v_pk_mul_f32 v[28:29], v[28:29], v[130:131] op_sel_hi:[1,0]
	v_pk_mul_f32 v[30:31], v[30:31], v[130:131] op_sel_hi:[1,0]
	v_pk_mul_f32 v[24:25], v[24:25], v[130:131] op_sel_hi:[1,0]
	v_pk_mul_f32 v[26:27], v[26:27], v[130:131] op_sel_hi:[1,0]
	v_add_f32_e32 v129, v150, v151
	v_add_f32_e32 v133, v152, v153
	v_add_f32_e32 v129, v129, v154
	v_add_f32_e32 v133, v133, v155
	v_add_f32_e32 v129, v129, v156
	v_add_f32_e32 v133, v133, v157
	v_add_f32_e32 v129, v129, v133
	v_fma_f32 v131, v131, v130, v129
	v_cvt_pk_bf16_f32 v166, v150, v151
	v_cvt_pk_bf16_f32 v167, v152, v153
	v_cvt_pk_bf16_f32 v168, v154, v155
	v_cvt_pk_bf16_f32 v169, v156, v157
	s_nop 1
	v_mfma_f32_16x16x32_bf16 v[36:39], v[56:59], v[166:169], v[36:39]
	v_mfma_f32_16x16x32_bf16 v[32:35], v[60:63], v[166:169], v[32:35]
	v_mfma_f32_16x16x32_bf16 v[28:31], v[64:67], v[166:169], v[28:31]
	v_mfma_f32_16x16x32_bf16 v[24:27], v[68:71], v[166:169], v[24:27]
.Lsc_skip:
	s_xor_b32 s7, s7, 0x4800
	s_cmp_lt_i32 s8, 0
	s_cbranch_scc1 .Lsc_nowrite
	v_add_u32_e32 v99, s7, v94
	s_waitcnt vmcnt(0)
	ds_write_b128 v99, v[72:75] offset:20480
	ds_write_b128 v99, v[76:79] offset:25088
	ds_write_b128 v99, v[80:83] offset:29696
	ds_write_b128 v99, v[84:87] offset:34304
.Lsc_nowrite:
	s_waitcnt lgkmcnt(0)
	s_barrier
	s_mov_b32 s5, s8
	s_cmp_lt_i32 s8, 0
	s_cbranch_scc0 .Lsc_loop
	s_waitcnt vmcnt(0) lgkmcnt(0)
	s_mov_b64 s[58:59], exec
